# attention second item: non-diagonal tiles take an unmasked softmax path (same math, masking instructions skipped)
# speedup vs baseline: 1.0317x; 1.0010x over previous
; #define LAS __attribute__((address_space(3)))
; DI unsigned pk2(float lo, float hi) { f32x2 v = {lo, hi}; bf2_t b = __builtin_convertvector(v, bf2_t); return __builtin_bit_cast(unsigned, b); }
; DI float fexp2(float x) { return __builtin_amdgcn_exp2f(x); }
; DI void attn_item(LAS unsigned char* lds, int bh, int qb, const bf16_t* QH, const bf16_t* KN, const bf16_t* KPE, const bf16_t* VT, const bf16_t* P, bf16_t* MIX) {
;     ...
;         float ps = 0.f;
; #pragma unroll
;         for (int i = 0; i < 16; ++i) { float p = fexp2(S[i] - mrow); if (diag && S[i] == NEG) p = 0.f; S[i] = p; ps += p; }
;         lrow += ps;
;         bf16x8 pb[2];
; #pragma unroll
;         for (int s2 = 0; s2 < 2; ++s2) { u32x4 w; w.x = pk2(S[8 * s2 + 0], S[8 * s2 + 1]); w.y = pk2(S[8 * s2 + 2], S[8 * s2 + 3]); w.z = pk2(S[8 * s2 + 4], S[8 * s2 + 5]); w.w = pk2(S[8 * s2 + 6], S[8 * s2 + 7]); pb[s2] = __builtin_bit_cast(bf16x8, w); }
;         __builtin_amdgcn_s_setprio(1);
;         {
;             const int li = lane & 15, gd = (lane >> 4) & 1;
;             const LAS unsigned char* vp = vb + (kh * 32 + 4 * h2 + (li >> 2)) * VROW + gd * 32 + (li & 3) * 8;
; #pragma unroll
;             for (int d = 0; d < 4; ++d)
; #pragma unroll
;                 for (int s2 = 0; s2 < 2; ++s2) {
;                     const s16x4 lo = __builtin_amdgcn_ds_read_tr16_b64_v4i16((LAS s16x4*)(vp + (16 * s2) * VROW + 64 * d));
;                     const s16x4 hi = __builtin_amdgcn_ds_read_tr16_b64_v4i16((LAS s16x4*)(vp + (16 * s2 + 8) * VROW + 64 * d));
;                     const bf16x8 av = __builtin_shufflevector(lo, hi, 0, 1, 2, 3, 4, 5, 6, 7);
;                     O[d] = __builtin_amdgcn_mfma_f32_32x32x16_bf16(av, pb[s2], O[d], 0, 0, 0);
;                 }
;         }
;         __builtin_amdgcn_s_setprio(0);
.Lsel609:
	s_cmp_lg_u64 s[20:21], 0
	s_cbranch_scc1 .LBB0_609
.Lfast609:
	v_sub_f32_e32 v185, v64, v200
	v_exp_f32_e32 v185, v185
	v_sub_f32_e32 v64, v65, v200
	v_exp_f32_e32 v64, v64
	v_sub_f32_e32 v65, v66, v200
	v_exp_f32_e32 v65, v65
	v_sub_f32_e32 v66, v67, v200
	v_exp_f32_e32 v66, v66
	v_sub_f32_e32 v67, v68, v200
	v_exp_f32_e32 v67, v67
	v_sub_f32_e32 v68, v69, v200
	v_exp_f32_e32 v68, v68
	v_sub_f32_e32 v69, v70, v200
	v_exp_f32_e32 v69, v69
	v_sub_f32_e32 v70, v71, v200
	v_exp_f32_e32 v70, v70
	v_sub_f32_e32 v71, v72, v200
	v_exp_f32_e32 v71, v71
	v_sub_f32_e32 v72, v73, v200
	v_add_f32_e32 v187, 0, v185
	v_exp_f32_e32 v72, v72
	v_add_f32_e32 v187, v64, v187
	v_add_f32_e32 v187, v65, v187
	v_sub_f32_e32 v73, v74, v200
	v_add_f32_e32 v187, v66, v187
	v_exp_f32_e32 v73, v73
	v_sub_f32_e32 v74, v75, v200
	v_add_f32_e32 v187, v67, v187
	v_exp_f32_e32 v74, v74
	v_sub_f32_e32 v75, v76, v200
	v_add_f32_e32 v187, v68, v187
	v_exp_f32_e32 v75, v75
	v_add_f32_e32 v187, v69, v187
	v_add_f32_e32 v187, v70, v187
	v_sub_f32_e32 v76, v77, v200
	v_add_f32_e32 v187, v71, v187
	v_exp_f32_e32 v76, v76
	v_sub_f32_e32 v77, v78, v200
	v_add_f32_e32 v187, v72, v187
	v_exp_f32_e32 v77, v77
	v_sub_f32_e32 v78, v79, v200
	v_add_f32_e32 v187, v73, v187
	v_exp_f32_e32 v78, v78
	v_add_f32_e32 v187, v74, v187
	v_add_f32_e32 v187, v75, v187
	v_add_f32_e32 v187, v76, v187
	v_add_f32_e32 v187, v77, v187
	v_add_f32_e32 v79, v78, v187
	v_cvt_pk_bf16_f32 v64, v185, v64
	v_cvt_pk_bf16_f32 v65, v65, v66
	v_cvt_pk_bf16_f32 v66, v67, v68
	v_cvt_pk_bf16_f32 v67, v69, v70
	v_cvt_pk_bf16_f32 v68, v71, v72
	v_cvt_pk_bf16_f32 v69, v73, v74
	v_cvt_pk_bf16_f32 v70, v75, v76
	v_cvt_pk_bf16_f32 v71, v77, v78
	s_setprio 1
	v_add_u32_e32 v72, s45, v201
	v_add3_u32 v78, v72, v225, v226
	ds_read_b64_tr_b16 v[72:73], v78 offset:25600
	ds_read_b64_tr_b16 v[74:75], v78 offset:28160
	ds_read_b64_tr_b16 v[76:77], v78 offset:33280
	ds_read_b64_tr_b16 v[206:207], v78 offset:25664
	ds_read_b64_tr_b16 v[210:211], v78 offset:25728
	ds_read_b64_tr_b16 v[214:215], v78 offset:25792
	ds_read_b64_tr_b16 v[208:209], v78 offset:28224
	ds_read_b64_tr_b16 v[212:213], v78 offset:28288
	ds_read_b64_tr_b16 v[216:217], v78 offset:28352
	s_waitcnt lgkmcnt(7)
	v_mfma_f32_32x32x16_bf16 v[48:63], v[72:75], v[64:67], v[48:63]
	ds_read_b64_tr_b16 v[74:75], v78 offset:30720
	ds_read_b64_tr_b16 v[232:233], v78 offset:30784
	ds_read_b64_tr_b16 v[236:237], v78 offset:30848
	ds_read_b64_tr_b16 v[240:241], v78 offset:30912
	ds_read_b64_tr_b16 v[234:235], v78 offset:33344
	ds_read_b64_tr_b16 v[238:239], v78 offset:33408
	ds_read_b64_tr_b16 v[242:243], v78 offset:33472
	v_add_f32_e32 v183, v183, v79
	s_waitcnt lgkmcnt(9)
	v_mfma_f32_32x32x16_bf16 v[32:47], v[206:209], v[64:67], v[32:47]
	s_waitcnt lgkmcnt(8)
	v_mfma_f32_32x32x16_bf16 v[16:31], v[210:213], v[64:67], v[16:31]
	s_waitcnt lgkmcnt(7)
	v_mfma_f32_32x32x16_bf16 v[0:15], v[214:217], v[64:67], v[0:15]
	s_waitcnt lgkmcnt(6)
	v_mfma_f32_32x32x16_bf16 v[48:63], v[74:77], v[68:71], v[48:63]
	s_waitcnt lgkmcnt(2)
	v_mfma_f32_32x32x16_bf16 v[32:47], v[232:235], v[68:71], v[32:47]
	s_waitcnt lgkmcnt(1)
	v_mfma_f32_32x32x16_bf16 v[16:31], v[236:239], v[68:71], v[16:31]
	s_waitcnt lgkmcnt(0)
	v_mfma_f32_32x32x16_bf16 v[0:15], v[240:243], v[68:71], v[0:15]
	s_setprio 0
	s_add_i32 s43, s43, 64
	s_add_u32 s18, s18, 1
	s_addc_u32 s19, s19, 0
	v_lshl_add_u64 v[196:197], v[196:197], 0, s[10:11]
	s_cmp_eq_u32 s44, s43
	v_lshl_add_u64 v[198:199], v[198:199], 0, s[10:11]
	s_cbranch_scc1 .LBB0_616
	s_branch .LBB0_610
